# norm phase row reductions: xor-32 and xor-16 steps via v_permlane32_swap / v_permlane16_swap instead of ds_bpermute round trips (bitwise identical sums)
# baseline (speedup 1.0000x reference)
; NI void phase_norm(const P& p, int l, unsigned* ctr, int* s_item, char* lds) {
;     ...
;     for (int rr = 0; rr < 4; ++rr) {
;       const float* xp = xrow_ptr(p, l, t0 + rr) + tid * 8;
;       v0[rr] = *(const float4*)xp; v1[rr] = *(const float4*)(xp + 4);
;     }
;     const float* md = mod + (t0 < NCTX ? 6144 : 0);
;     float wv[8], sc[8], sh[8];
; #pragma unroll
;     for (int i = 0; i < 8; ++i) { const int c0 = tid * 8 + i; wv[i] = nw[c0]; sc[i] = 1.f + md[2048 + c0]; sh[i] = md[c0]; }
; #pragma unroll
;     for (int rr = 0; rr < 4; ++rr) {
;       float ss = v0[rr].x * v0[rr].x + v0[rr].y * v0[rr].y + v0[rr].z * v0[rr].z + v0[rr].w * v0[rr].w +
;                  v1[rr].x * v1[rr].x + v1[rr].y * v1[rr].y + v1[rr].z * v1[rr].z + v1[rr].w * v1[rr].w;
;       ss += __shfl_xor(ss, 32); ss = hw_sum(ss);
;       if ((tid & 63) == 0) red[rr * 4 + (tid >> 6)] = ss;
;     }
.LBB0_510:
	s_lshl_b64 s[0:1], s[0:1], 13
	s_add_u32 s0, s18, s0
	s_addc_u32 s1, s19, s1
	s_cmp_lt_i32 s36, 64
	s_cselect_b32 s74, 0x6000, 0
	v_lshl_add_u64 v[44:45], v[62:63], 0, s[74:75]
	v_lshl_add_u64 v[28:29], v[56:57], 2, s[0:1]
	v_add_co_u32_e32 v30, vcc, s33, v44
	global_load_dwordx4 v[24:27], v[28:29], off offset:16
	global_load_dwordx4 v[36:39], v[28:29], off
	v_lshl_add_u64 v[28:29], v[44:45], 0, s[72:73]
	v_addc_co_u32_e32 v31, vcc, 0, v45, vcc
	global_load_dwordx4 v[52:55], v[30:31], off
	global_load_dwordx4 v[48:51], v[28:29], off offset:16
	s_nop 0
	global_load_dwordx4 v[28:31], v[60:61], off offset:16
	global_load_dwordx4 v[40:43], v[60:61], off
	global_load_dwordx4 v[32:35], v[44:45], off offset:16
	s_nop 0
	global_load_dwordx4 v[44:47], v[44:45], off
	s_waitcnt vmcnt(12)
	v_pk_mul_f32 v[66:67], v[4:5], v[4:5]
	v_pk_mul_f32 v[64:65], v[6:7], v[6:7]
	v_add_f32_e32 v66, v66, v67
	v_add_f32_e32 v64, v66, v64
	v_pk_mul_f32 v[78:79], v[0:1], v[0:1]
	v_add_f32_e32 v64, v64, v65
	v_add_f32_e32 v64, v64, v78
	v_pk_mul_f32 v[76:77], v[2:3], v[2:3]
	v_add_f32_e32 v64, v64, v79
	v_add_f32_e32 v64, v64, v76
	v_add_f32_e32 v64, v64, v77
	v_mov_b32_e32 v65, v64
	v_mov_b32_e32 v98, v64
	s_nop 1
	v_permlane32_swap_b32_e32 v65, v98
	v_add_f32_e32 v64, v65, v98
	v_mov_b32_e32 v65, v64
	v_mov_b32_e32 v98, v64
	s_nop 1
	v_permlane16_swap_b32_e32 v65, v98
	v_add_f32_e32 v64, v65, v98
	s_nop 1
	v_add_f32_dpp v64, v64, v64 row_ror:8 row_mask:0xf bank_mask:0xf
	s_nop 1
	v_add_f32_dpp v64, v64, v64 row_ror:4 row_mask:0xf bank_mask:0xf
	s_nop 1
	v_add_f32_dpp v64, v64, v64 row_ror:2 row_mask:0xf bank_mask:0xf
	ds_bpermute_b32 v65, v73, v64
	s_and_saveexec_b64 s[0:1], s[20:21]
	s_cbranch_execz .LBB0_512
	s_waitcnt lgkmcnt(0)
	v_add_f32_e32 v64, v64, v65
	ds_write_b32 v74, v64
.LBB0_512:
	s_or_b64 exec, exec, s[0:1]
	s_waitcnt vmcnt(10)
	v_pk_mul_f32 v[66:67], v[12:13], v[12:13]
	s_waitcnt lgkmcnt(0)
	v_pk_mul_f32 v[64:65], v[14:15], v[14:15]
	v_add_f32_e32 v66, v66, v67
	v_add_f32_e32 v64, v66, v64
	v_pk_mul_f32 v[78:79], v[8:9], v[8:9]
	v_add_f32_e32 v64, v64, v65
	v_add_f32_e32 v64, v64, v78
	v_pk_mul_f32 v[76:77], v[10:11], v[10:11]
	v_add_f32_e32 v64, v64, v79
	v_add_f32_e32 v64, v64, v76
	v_add_f32_e32 v64, v64, v77
	v_mov_b32_e32 v65, v64
	v_mov_b32_e32 v98, v64
	s_nop 1
	v_permlane32_swap_b32_e32 v65, v98
	v_add_f32_e32 v64, v65, v98
	v_mov_b32_e32 v65, v64
	v_mov_b32_e32 v98, v64
	s_nop 1
	v_permlane16_swap_b32_e32 v65, v98
	v_add_f32_e32 v64, v65, v98
	s_nop 1
	v_add_f32_dpp v64, v64, v64 row_ror:8 row_mask:0xf bank_mask:0xf
	s_nop 1
	v_add_f32_dpp v64, v64, v64 row_ror:4 row_mask:0xf bank_mask:0xf
	s_nop 1
	v_add_f32_dpp v64, v64, v64 row_ror:2 row_mask:0xf bank_mask:0xf
	ds_bpermute_b32 v65, v73, v64
	s_and_saveexec_b64 s[0:1], s[20:21]
	s_cbranch_execz .LBB0_514
	s_waitcnt lgkmcnt(0)
	v_add_f32_e32 v64, v64, v65
	ds_write_b32 v74, v64 offset:16
.LBB0_514:
	s_or_b64 exec, exec, s[0:1]
	s_waitcnt vmcnt(8)
	v_pk_mul_f32 v[66:67], v[20:21], v[20:21]
	s_waitcnt lgkmcnt(0)
	v_pk_mul_f32 v[64:65], v[22:23], v[22:23]
	v_add_f32_e32 v66, v66, v67
	v_add_f32_e32 v64, v66, v64
	v_pk_mul_f32 v[78:79], v[16:17], v[16:17]
	v_add_f32_e32 v64, v64, v65
	v_add_f32_e32 v64, v64, v78
	v_pk_mul_f32 v[76:77], v[18:19], v[18:19]
	v_add_f32_e32 v64, v64, v79
	v_add_f32_e32 v64, v64, v76
	v_add_f32_e32 v64, v64, v77
	v_mov_b32_e32 v65, v64
	v_mov_b32_e32 v98, v64
	s_nop 1
	v_permlane32_swap_b32_e32 v65, v98
	v_add_f32_e32 v64, v65, v98
	v_mov_b32_e32 v65, v64
	v_mov_b32_e32 v98, v64
	s_nop 1
	v_permlane16_swap_b32_e32 v65, v98
	v_add_f32_e32 v64, v65, v98
	s_nop 1
	v_add_f32_dpp v64, v64, v64 row_ror:8 row_mask:0xf bank_mask:0xf
	s_nop 1
	v_add_f32_dpp v64, v64, v64 row_ror:4 row_mask:0xf bank_mask:0xf
	s_nop 1
	v_add_f32_dpp v64, v64, v64 row_ror:2 row_mask:0xf bank_mask:0xf
	ds_bpermute_b32 v65, v73, v64
	s_and_saveexec_b64 s[0:1], s[20:21]
	s_cbranch_execz .LBB0_516
	s_waitcnt lgkmcnt(0)
	v_add_f32_e32 v64, v64, v65
	ds_write_b32 v74, v64 offset:32
.LBB0_516:
	s_or_b64 exec, exec, s[0:1]
	s_waitcnt vmcnt(6)
	v_pk_mul_f32 v[66:67], v[36:37], v[36:37]
	s_waitcnt lgkmcnt(0)
	v_pk_mul_f32 v[64:65], v[38:39], v[38:39]
	v_add_f32_e32 v66, v66, v67
	v_add_f32_e32 v64, v66, v64
	v_pk_mul_f32 v[78:79], v[24:25], v[24:25]
	v_add_f32_e32 v64, v64, v65
	v_add_f32_e32 v64, v64, v78
	v_pk_mul_f32 v[76:77], v[26:27], v[26:27]
	v_add_f32_e32 v64, v64, v79
	v_add_f32_e32 v64, v64, v76
	v_add_f32_e32 v64, v64, v77
	v_mov_b32_e32 v65, v64
	v_mov_b32_e32 v98, v64
	s_nop 1
	v_permlane32_swap_b32_e32 v65, v98
	v_add_f32_e32 v64, v65, v98
	v_mov_b32_e32 v65, v64
	v_mov_b32_e32 v98, v64
	s_nop 1
	v_permlane16_swap_b32_e32 v65, v98
	v_add_f32_e32 v64, v65, v98
	s_nop 1
	v_add_f32_dpp v64, v64, v64 row_ror:8 row_mask:0xf bank_mask:0xf
	s_nop 1
	v_add_f32_dpp v64, v64, v64 row_ror:4 row_mask:0xf bank_mask:0xf
	s_nop 1
	v_add_f32_dpp v64, v64, v64 row_ror:2 row_mask:0xf bank_mask:0xf
	ds_bpermute_b32 v65, v73, v64
	s_and_saveexec_b64 s[0:1], s[20:21]
	s_cbranch_execz .LBB0_477
	s_waitcnt lgkmcnt(0)
	v_add_f32_e32 v64, v64, v65
	ds_write_b32 v74, v64 offset:48
	s_branch .LBB0_477
